# v85 + each workgroup sums only its own batch's 512 adaLN quads (global copy written by workgroups 0..5): 1 pass instead of 6 serial passes
# speedup vs baseline: 1.0132x; 1.0005x over previous
.LBB0_78:
	s_or_b64 exec, exec, s[6:7]
	s_load_dwordx16 s[52:67], s[0:1], 0x40
	s_waitcnt lgkmcnt(0)
	v_mov_b32_e32 v0, v234
	s_barrier
	v_writelane_b32 v253, s52, 5
	s_nop 0
	v_bfi_b32 v8, 63, v0, s73
	v_writelane_b32 v253, s53, 6
	v_writelane_b32 v253, s54, 7
	v_writelane_b32 v253, s55, 8
	v_writelane_b32 v253, s56, 9
	v_writelane_b32 v253, s57, 10
	v_writelane_b32 v253, s58, 11
	v_writelane_b32 v253, s59, 12
	v_writelane_b32 v253, s60, 13
	v_writelane_b32 v253, s61, 14
	v_writelane_b32 v253, s62, 15
	v_writelane_b32 v253, s63, 16
	v_writelane_b32 v253, s64, 17
	v_writelane_b32 v253, s65, 18
	v_writelane_b32 v253, s66, 19
	v_writelane_b32 v253, s67, 20
	s_load_dwordx16 s[52:67], s[0:1], 0x80
	s_movk_i32 s0, 0xc00
	v_cmp_gt_i32_e32 vcc, s0, v8
	s_and_saveexec_b64 s[6:7], vcc
	s_cbranch_execz .LBB0_83
	s_lshr_b32 s98, s77, 6
	s_mulk_i32 s98, 0x300
	v_add_u32_e32 v8, s98, v8
	s_lshl_b32 s99, s77, 9
	s_lshl_b32 s101, s99, 4
	s_lshl_b32 s98, s99, 2
	s_add_i32 s100, s77, -1
	s_cmp_lt_u32 s100, 5
	s_cselect_b32 s100, 0x1ff, -1
	s_cmp_lt_u32 s77, 6
	s_cselect_b64 s[0:1], -1, 0
	v_cndmask_b32_e64 v0, 0, 1, s[0:1]
	v_lshl_add_u32 v9, v8, 4, 0
	v_lshlrev_b32_e32 v10, 2, v8
	s_mov_b64 s[8:9], 0
	s_mov_b32 s2, 0x2aaaaaab
	s_mov_b32 s3, 0xc000
	s_mov_b32 s10, 0x18000
	s_mov_b32 s11, 0x24000
	s_mov_b32 s12, 0x30000
	s_mov_b32 s13, 0x3c000
	s_mov_b32 s14, 0x48000
	v_cmp_ne_u32_e64 s[0:1], 1, v0
	s_mov_b32 s15, s100
	s_branch .LBB0_81
.LBB0_80:
	s_nop 0
	v_add_u32_e32 v0, s99, v8
	v_cmp_lt_i32_e32 vcc, s15, v8
	v_add_u32_e32 v9, s101, v9
	v_add_u32_e32 v10, s98, v10
	s_or_b64 s[8:9], vcc, s[8:9]
	v_mov_b32_e32 v8, v0
	s_andn2_b64 exec, exec, s[8:9]
	s_cbranch_execz .LBB0_83
